# conv3+SiLU strips: prefetch ring shortened from 4 to 2 rows in flight per thread (8 in flight was slower)
# baseline (speedup 1.0000x reference)
.LBB0_893:
	s_cmp_lt_i32 s64, 10
	s_cselect_b64 s[4:5], -1, 0
	s_and_b64 s[0:1], s[4:5], s[2:3]
	s_andn2_b64 vcc, exec, s[0:1]
	s_cbranch_vccnz .LBB0_906
	s_lshl_b32 s8, s88, 9
	s_waitcnt vmcnt(0)
	v_or_b32_e32 v1, s8, v0
	s_mov_b32 s0, 0x158000
	v_cmp_gt_i32_e32 vcc, s0, v1
	s_and_saveexec_b64 s[6:7], vcc
	s_cbranch_execz .LBB0_905
	s_waitcnt vmcnt(0) lgkmcnt(0)
	v_lshrrev_b32_e32 v1, 6, v0
	v_lshlrev_b32_e32 v1, 14, v1
	v_and_b32_e32 v2, 63, v0
	v_lshl_or_b32 v1, v2, 4, v1
	ds_write_b128 v1, v[138:141]
	ds_write_b128 v1, v[142:145] offset:1024
	ds_write_b128 v1, v[146:149] offset:2048
	ds_write_b128 v1, v[150:153] offset:3072
	ds_write_b128 v1, v[154:157] offset:4096
	ds_write_b128 v1, v[158:161] offset:5120
	ds_write_b128 v1, v[162:165] offset:6144
	ds_write_b128 v1, v[166:169] offset:7168
	ds_write_b128 v1, v[170:173] offset:8192
	ds_write_b128 v1, v[174:177] offset:9216
	ds_write_b128 v1, v[178:181] offset:10240
	ds_write_b128 v1, v[182:185] offset:11264
	ds_write_b128 v1, v[186:189] offset:12288
	ds_write_b128 v1, v[190:193] offset:13312
	ds_write_b128 v1, v[194:197] offset:14336
	ds_write_b128 v1, v[198:201] offset:15360
	v_readlane_b32 s24, v247, 3
	v_readlane_b32 s25, v247, 4
	s_load_dwordx4 s[8:11], s[24:25], 0xd0
	s_waitcnt lgkmcnt(0)
	s_add_u32 s12, s10, 0x0
	s_addc_u32 s13, s11, 0
	s_add_u32 s14, s12, 0xac00
	s_addc_u32 s15, s13, 0
	s_add_u32 s8, s8, 0x0
	s_addc_u32 s9, s9, 0
	s_add_u32 s10, s8, 0xac00
	s_addc_u32 s11, s9, 0
	s_mov_b64 s[16:17], s[70:71]
	s_add_u32 s18, s70, 0x5600
	s_addc_u32 s19, s71, 0
	s_add_u32 s20, s94, 0x72500000
	s_addc_u32 s21, s95, 0
	s_mov_b32 s23, 0x56000
	s_mov_b32 s28, 0x2b000
	s_mov_b32 s22, 11
	s_lshl_b32 s24, s88, 9
	v_add_u32_e32 v1, s24, v0
	v_lshrrev_b32_e32 v175, 5, v1
	v_mov_b32_e32 v178, 0xbe83
	v_mul_lo_u32 v175, v175, v178
	v_lshrrev_b32_e32 v175, 21, v175
	v_mul_u32_u24_e32 v178, 0x560, v175
	v_sub_u32_e32 v170, v1, v178
	v_min_u32_e32 v175, 94, v175
	v_mul_u32_u24_e32 v175, 0xac7, v175
	v_lshrrev_b32_e32 v171, 8, v175
	v_lshlrev_b32_e32 v175, 4, v170
	v_mad_u32_u24 v172, v171, s23, v175
	v_mad_u32_u24 v173, v171, s28, v175
	v_lshlrev_b32_e32 v174, 5, v170
	v_add_u32_e32 v176, 0x15800, v174
	v_add_u32_e32 v177, 0x2b000, v174
	global_load_dwordx4 v[2:5], v174, s[8:9]
	global_load_dwordx4 v[6:9], v174, s[8:9] offset:16
	global_load_dwordx4 v[10:13], v176, s[8:9]
	global_load_dwordx4 v[14:17], v176, s[8:9] offset:16
	global_load_dwordx4 v[18:21], v177, s[8:9]
	global_load_dwordx4 v[22:25], v177, s[8:9] offset:16
	global_load_dwordx4 v[50:53], v174, s[12:13]
	global_load_dwordx4 v[54:57], v174, s[12:13] offset:16
	global_load_dwordx4 v[26:29], v174, s[10:11]
	global_load_dwordx4 v[30:33], v174, s[10:11] offset:16
	global_load_dwordx4 v[34:37], v176, s[10:11]
	global_load_dwordx4 v[38:41], v176, s[10:11] offset:16
	global_load_dwordx4 v[42:45], v177, s[10:11]
	global_load_dwordx4 v[46:49], v177, s[10:11] offset:16
	global_load_dwordx4 v[58:61], v174, s[14:15]
	global_load_dwordx4 v[62:65], v174, s[14:15] offset:16
	v_and_b32_e32 v175, 0xff, v171
	v_cmp_ne_u32_e32 vcc, 0, v175
	v_mov_b32_e32 v178, 0x15800
	s_nop 0
	v_cndmask_b32_e32 v175, 0, v178, vcc
	v_sub_u32_e32 v176, v172, v175
	v_lshrrev_b32_e32 v175, 1, v175
	v_sub_u32_e32 v177, v172, v175
	global_load_dwordx4 v[66:69], v176, s[16:17] nt
	global_load_dwordx4 v[70:73], v176, s[18:19] nt
	global_load_dwordx4 v[74:77], v177, s[16:17] nt
	global_load_dwordx4 v[78:81], v177, s[18:19] nt
	s_waitcnt vmcnt(0)
	v_lshlrev_b32_e32 v98, 16, v66
	v_and_b32_e32 v99, 0xffff0000, v66
	v_lshlrev_b32_e32 v100, 16, v67
	v_and_b32_e32 v101, 0xffff0000, v67
	v_lshlrev_b32_e32 v102, 16, v68
	v_and_b32_e32 v103, 0xffff0000, v68
	v_lshlrev_b32_e32 v104, 16, v69
	v_and_b32_e32 v105, 0xffff0000, v69
	v_lshlrev_b32_e32 v106, 16, v70
	v_and_b32_e32 v107, 0xffff0000, v70
	v_lshlrev_b32_e32 v108, 16, v71
	v_and_b32_e32 v109, 0xffff0000, v71
	v_lshlrev_b32_e32 v110, 16, v72
	v_and_b32_e32 v111, 0xffff0000, v72
	v_lshlrev_b32_e32 v112, 16, v73
	v_and_b32_e32 v113, 0xffff0000, v73
	v_lshlrev_b32_e32 v114, 16, v74
	v_and_b32_e32 v115, 0xffff0000, v74
	v_lshlrev_b32_e32 v116, 16, v75
	v_and_b32_e32 v117, 0xffff0000, v75
	v_lshlrev_b32_e32 v118, 16, v76
	v_and_b32_e32 v119, 0xffff0000, v76
	v_lshlrev_b32_e32 v120, 16, v77
	v_and_b32_e32 v121, 0xffff0000, v77
	v_lshlrev_b32_e32 v122, 16, v78
	v_and_b32_e32 v123, 0xffff0000, v78
	v_lshlrev_b32_e32 v124, 16, v79
	v_and_b32_e32 v125, 0xffff0000, v79
	v_lshlrev_b32_e32 v126, 16, v80
	v_and_b32_e32 v127, 0xffff0000, v80
	v_lshlrev_b32_e32 v128, 16, v81
	v_and_b32_e32 v129, 0xffff0000, v81
	global_load_dwordx4 v[66:69], v172, s[16:17] nt
	global_load_dwordx4 v[70:73], v172, s[18:19] nt
	v_add_u32_e32 v172, 0xac00, v172
	global_load_dwordx4 v[74:77], v172, s[16:17] nt
	global_load_dwordx4 v[78:81], v172, s[18:19] nt
	v_add_u32_e32 v172, 0xac00, v172
	s_waitcnt vmcnt(0)
.Lgrp_cy0:
	v_and_b32_e32 v175, 0xff, v171
	v_cmp_ne_u32_e64 s[24:25], 0, v175
	v_add_u32_e32 v171, 1, v171
	s_nop 3
	v_cndmask_b32_e64 v98, 0, v98, s[24:25]
	v_cndmask_b32_e64 v99, 0, v99, s[24:25]
	v_cndmask_b32_e64 v100, 0, v100, s[24:25]
	v_cndmask_b32_e64 v101, 0, v101, s[24:25]
	v_cndmask_b32_e64 v102, 0, v102, s[24:25]
	v_cndmask_b32_e64 v103, 0, v103, s[24:25]
	v_cndmask_b32_e64 v104, 0, v104, s[24:25]
	v_cndmask_b32_e64 v105, 0, v105, s[24:25]
	v_cndmask_b32_e64 v106, 0, v106, s[24:25]
	v_cndmask_b32_e64 v107, 0, v107, s[24:25]
	v_cndmask_b32_e64 v108, 0, v108, s[24:25]
	v_cndmask_b32_e64 v109, 0, v109, s[24:25]
	v_cndmask_b32_e64 v110, 0, v110, s[24:25]
	v_cndmask_b32_e64 v111, 0, v111, s[24:25]
	v_cndmask_b32_e64 v112, 0, v112, s[24:25]
	v_cndmask_b32_e64 v113, 0, v113, s[24:25]
	v_cndmask_b32_e64 v114, 0, v114, s[24:25]
	v_cndmask_b32_e64 v115, 0, v115, s[24:25]
	v_cndmask_b32_e64 v116, 0, v116, s[24:25]
	v_cndmask_b32_e64 v117, 0, v117, s[24:25]
	v_cndmask_b32_e64 v118, 0, v118, s[24:25]
	v_cndmask_b32_e64 v119, 0, v119, s[24:25]
	v_cndmask_b32_e64 v120, 0, v120, s[24:25]
	v_cndmask_b32_e64 v121, 0, v121, s[24:25]
	v_cndmask_b32_e64 v122, 0, v122, s[24:25]
	v_cndmask_b32_e64 v123, 0, v123, s[24:25]
	v_cndmask_b32_e64 v124, 0, v124, s[24:25]
	v_cndmask_b32_e64 v125, 0, v125, s[24:25]
	v_cndmask_b32_e64 v126, 0, v126, s[24:25]
	v_cndmask_b32_e64 v127, 0, v127, s[24:25]
	v_cndmask_b32_e64 v128, 0, v128, s[24:25]
	v_cndmask_b32_e64 v129, 0, v129, s[24:25]
	s_waitcnt vmcnt(4)
	v_lshlrev_b32_e32 v130, 16, v66
	v_and_b32_e32 v131, 0xffff0000, v66
	v_lshlrev_b32_e32 v132, 16, v67
	v_and_b32_e32 v133, 0xffff0000, v67
	v_lshlrev_b32_e32 v134, 16, v68
	v_and_b32_e32 v135, 0xffff0000, v68
	v_lshlrev_b32_e32 v136, 16, v69
	v_and_b32_e32 v137, 0xffff0000, v69
	v_lshlrev_b32_e32 v138, 16, v70
	v_and_b32_e32 v139, 0xffff0000, v70
	v_lshlrev_b32_e32 v140, 16, v71
	v_and_b32_e32 v141, 0xffff0000, v71
	v_lshlrev_b32_e32 v142, 16, v72
	v_and_b32_e32 v143, 0xffff0000, v72
	v_lshlrev_b32_e32 v144, 16, v73
	v_and_b32_e32 v145, 0xffff0000, v73
	global_load_dwordx4 v[66:69], v172, s[16:17] nt
	global_load_dwordx4 v[70:73], v172, s[18:19] nt
	v_add_u32_e32 v172, 0xac00, v172
	v_pk_fma_f32 v[146:147], v[2:3], v[98:99], v[50:51]
	v_pk_fma_f32 v[148:149], v[4:5], v[100:101], v[52:53]
	v_pk_fma_f32 v[150:151], v[6:7], v[102:103], v[54:55]
	v_pk_fma_f32 v[152:153], v[8:9], v[104:105], v[56:57]
	v_pk_fma_f32 v[154:155], v[26:27], v[106:107], v[58:59]
	v_pk_fma_f32 v[156:157], v[28:29], v[108:109], v[60:61]
	v_pk_fma_f32 v[158:159], v[30:31], v[110:111], v[62:63]
	v_pk_fma_f32 v[160:161], v[32:33], v[112:113], v[64:65]
	v_pk_fma_f32 v[146:147], v[10:11], v[114:115], v[146:147]
	v_pk_fma_f32 v[148:149], v[12:13], v[116:117], v[148:149]
	v_pk_fma_f32 v[150:151], v[14:15], v[118:119], v[150:151]
	v_pk_fma_f32 v[152:153], v[16:17], v[120:121], v[152:153]
	v_pk_fma_f32 v[154:155], v[34:35], v[122:123], v[154:155]
	v_pk_fma_f32 v[156:157], v[36:37], v[124:125], v[156:157]
	v_pk_fma_f32 v[158:159], v[38:39], v[126:127], v[158:159]
	v_pk_fma_f32 v[160:161], v[40:41], v[128:129], v[160:161]
	v_pk_fma_f32 v[146:147], v[18:19], v[130:131], v[146:147]
	v_pk_fma_f32 v[148:149], v[20:21], v[132:133], v[148:149]
	v_pk_fma_f32 v[150:151], v[22:23], v[134:135], v[150:151]
	v_pk_fma_f32 v[152:153], v[24:25], v[136:137], v[152:153]
	v_pk_fma_f32 v[154:155], v[42:43], v[138:139], v[154:155]
	v_pk_fma_f32 v[156:157], v[44:45], v[140:141], v[156:157]
	v_pk_fma_f32 v[158:159], v[46:47], v[142:143], v[158:159]
	v_pk_fma_f32 v[160:161], v[48:49], v[144:145], v[160:161]
	v_mul_f32_e32 v162, 0xbfb8aa3b, v146
	v_mul_f32_e32 v163, 0xbfb8aa3b, v147
	v_mul_f32_e32 v164, 0xbfb8aa3b, v148
	v_mul_f32_e32 v165, 0xbfb8aa3b, v149
	v_mul_f32_e32 v166, 0xbfb8aa3b, v150
	v_mul_f32_e32 v167, 0xbfb8aa3b, v151
	v_mul_f32_e32 v168, 0xbfb8aa3b, v152
	v_mul_f32_e32 v169, 0xbfb8aa3b, v153
	v_exp_f32_e32 v162, v162
	v_exp_f32_e32 v163, v163
	v_exp_f32_e32 v164, v164
	v_exp_f32_e32 v165, v165
	v_exp_f32_e32 v166, v166
	v_exp_f32_e32 v167, v167
	v_exp_f32_e32 v168, v168
	v_exp_f32_e32 v169, v169
	v_add_f32_e32 v162, 1.0, v162
	v_add_f32_e32 v163, 1.0, v163
	v_add_f32_e32 v164, 1.0, v164
	v_add_f32_e32 v165, 1.0, v165
	v_add_f32_e32 v166, 1.0, v166
	v_add_f32_e32 v167, 1.0, v167
	v_add_f32_e32 v168, 1.0, v168
	v_add_f32_e32 v169, 1.0, v169
	v_rcp_f32_e32 v162, v162
	v_rcp_f32_e32 v163, v163
	v_rcp_f32_e32 v164, v164
	v_rcp_f32_e32 v165, v165
	v_rcp_f32_e32 v166, v166
	v_rcp_f32_e32 v167, v167
	v_rcp_f32_e32 v168, v168
	v_rcp_f32_e32 v169, v169
	s_nop 0
	v_pk_mul_f32 v[146:147], v[146:147], v[162:163]
	v_pk_mul_f32 v[148:149], v[148:149], v[164:165]
	v_pk_mul_f32 v[150:151], v[150:151], v[166:167]
	v_pk_mul_f32 v[152:153], v[152:153], v[168:169]
	v_pk_mul_f32 v[146:147], v[154:155], v[146:147]
	v_pk_mul_f32 v[148:149], v[156:157], v[148:149]
	v_pk_mul_f32 v[150:151], v[158:159], v[150:151]
	v_pk_mul_f32 v[152:153], v[160:161], v[152:153]
	v_cvt_pk_bf16_f32 v162, v146, v147
	v_cvt_pk_bf16_f32 v163, v148, v149
	v_cvt_pk_bf16_f32 v164, v150, v151
	v_cvt_pk_bf16_f32 v165, v152, v153
	global_store_dwordx4 v173, v[162:165], s[20:21]
	v_add_u32_e32 v173, 0x5600, v173
	s_waitcnt vmcnt(4)
	v_lshlrev_b32_e32 v98, 16, v74
	v_and_b32_e32 v99, 0xffff0000, v74
	v_lshlrev_b32_e32 v100, 16, v75
	v_and_b32_e32 v101, 0xffff0000, v75
	v_lshlrev_b32_e32 v102, 16, v76
	v_and_b32_e32 v103, 0xffff0000, v76
	v_lshlrev_b32_e32 v104, 16, v77
	v_and_b32_e32 v105, 0xffff0000, v77
	v_lshlrev_b32_e32 v106, 16, v78
	v_and_b32_e32 v107, 0xffff0000, v78
	v_lshlrev_b32_e32 v108, 16, v79
	v_and_b32_e32 v109, 0xffff0000, v79
	v_lshlrev_b32_e32 v110, 16, v80
	v_and_b32_e32 v111, 0xffff0000, v80
	v_lshlrev_b32_e32 v112, 16, v81
	v_and_b32_e32 v113, 0xffff0000, v81
	global_load_dwordx4 v[74:77], v172, s[16:17] nt
	global_load_dwordx4 v[78:81], v172, s[18:19] nt
	v_add_u32_e32 v172, 0xac00, v172
	v_pk_fma_f32 v[146:147], v[2:3], v[114:115], v[50:51]
	v_pk_fma_f32 v[148:149], v[4:5], v[116:117], v[52:53]
	v_pk_fma_f32 v[150:151], v[6:7], v[118:119], v[54:55]
	v_pk_fma_f32 v[152:153], v[8:9], v[120:121], v[56:57]
	v_pk_fma_f32 v[154:155], v[26:27], v[122:123], v[58:59]
	v_pk_fma_f32 v[156:157], v[28:29], v[124:125], v[60:61]
	v_pk_fma_f32 v[158:159], v[30:31], v[126:127], v[62:63]
	v_pk_fma_f32 v[160:161], v[32:33], v[128:129], v[64:65]
	v_pk_fma_f32 v[146:147], v[10:11], v[130:131], v[146:147]
	v_pk_fma_f32 v[148:149], v[12:13], v[132:133], v[148:149]
	v_pk_fma_f32 v[150:151], v[14:15], v[134:135], v[150:151]
	v_pk_fma_f32 v[152:153], v[16:17], v[136:137], v[152:153]
	v_pk_fma_f32 v[154:155], v[34:35], v[138:139], v[154:155]
	v_pk_fma_f32 v[156:157], v[36:37], v[140:141], v[156:157]
	v_pk_fma_f32 v[158:159], v[38:39], v[142:143], v[158:159]
	v_pk_fma_f32 v[160:161], v[40:41], v[144:145], v[160:161]
	v_pk_fma_f32 v[146:147], v[18:19], v[98:99], v[146:147]
	v_pk_fma_f32 v[148:149], v[20:21], v[100:101], v[148:149]
	v_pk_fma_f32 v[150:151], v[22:23], v[102:103], v[150:151]
	v_pk_fma_f32 v[152:153], v[24:25], v[104:105], v[152:153]
	v_pk_fma_f32 v[154:155], v[42:43], v[106:107], v[154:155]
	v_pk_fma_f32 v[156:157], v[44:45], v[108:109], v[156:157]
	v_pk_fma_f32 v[158:159], v[46:47], v[110:111], v[158:159]
	v_pk_fma_f32 v[160:161], v[48:49], v[112:113], v[160:161]
	v_mul_f32_e32 v162, 0xbfb8aa3b, v146
	v_mul_f32_e32 v163, 0xbfb8aa3b, v147
	v_mul_f32_e32 v164, 0xbfb8aa3b, v148
	v_mul_f32_e32 v165, 0xbfb8aa3b, v149
	v_mul_f32_e32 v166, 0xbfb8aa3b, v150
	v_mul_f32_e32 v167, 0xbfb8aa3b, v151
	v_mul_f32_e32 v168, 0xbfb8aa3b, v152
	v_mul_f32_e32 v169, 0xbfb8aa3b, v153
	v_exp_f32_e32 v162, v162
	v_exp_f32_e32 v163, v163
	v_exp_f32_e32 v164, v164
	v_exp_f32_e32 v165, v165
	v_exp_f32_e32 v166, v166
	v_exp_f32_e32 v167, v167
	v_exp_f32_e32 v168, v168
	v_exp_f32_e32 v169, v169
	v_add_f32_e32 v162, 1.0, v162
	v_add_f32_e32 v163, 1.0, v163
	v_add_f32_e32 v164, 1.0, v164
	v_add_f32_e32 v165, 1.0, v165
	v_add_f32_e32 v166, 1.0, v166
	v_add_f32_e32 v167, 1.0, v167
	v_add_f32_e32 v168, 1.0, v168
	v_add_f32_e32 v169, 1.0, v169
	v_rcp_f32_e32 v162, v162
	v_rcp_f32_e32 v163, v163
	v_rcp_f32_e32 v164, v164
	v_rcp_f32_e32 v165, v165
	v_rcp_f32_e32 v166, v166
	v_rcp_f32_e32 v167, v167
	v_rcp_f32_e32 v168, v168
	v_rcp_f32_e32 v169, v169
	s_nop 0
	v_pk_mul_f32 v[146:147], v[146:147], v[162:163]
	v_pk_mul_f32 v[148:149], v[148:149], v[164:165]
	v_pk_mul_f32 v[150:151], v[150:151], v[166:167]
	v_pk_mul_f32 v[152:153], v[152:153], v[168:169]
	v_pk_mul_f32 v[146:147], v[154:155], v[146:147]
	v_pk_mul_f32 v[148:149], v[156:157], v[148:149]
	v_pk_mul_f32 v[150:151], v[158:159], v[150:151]
	v_pk_mul_f32 v[152:153], v[160:161], v[152:153]
	v_cvt_pk_bf16_f32 v162, v146, v147
	v_cvt_pk_bf16_f32 v163, v148, v149
	v_cvt_pk_bf16_f32 v164, v150, v151
	v_cvt_pk_bf16_f32 v165, v152, v153
	global_store_dwordx4 v173, v[162:165], s[20:21]
	v_add_u32_e32 v173, 0x5600, v173
	s_waitcnt vmcnt(4)
	v_lshlrev_b32_e32 v114, 16, v66
	v_and_b32_e32 v115, 0xffff0000, v66
	v_lshlrev_b32_e32 v116, 16, v67
	v_and_b32_e32 v117, 0xffff0000, v67
	v_lshlrev_b32_e32 v118, 16, v68
	v_and_b32_e32 v119, 0xffff0000, v68
	v_lshlrev_b32_e32 v120, 16, v69
	v_and_b32_e32 v121, 0xffff0000, v69
	v_lshlrev_b32_e32 v122, 16, v70
	v_and_b32_e32 v123, 0xffff0000, v70
	v_lshlrev_b32_e32 v124, 16, v71
	v_and_b32_e32 v125, 0xffff0000, v71
	v_lshlrev_b32_e32 v126, 16, v72
	v_and_b32_e32 v127, 0xffff0000, v72
	v_lshlrev_b32_e32 v128, 16, v73
	v_and_b32_e32 v129, 0xffff0000, v73
	global_load_dwordx4 v[66:69], v172, s[16:17] nt
	global_load_dwordx4 v[70:73], v172, s[18:19] nt
	v_add_u32_e32 v172, 0xac00, v172
	v_pk_fma_f32 v[146:147], v[2:3], v[130:131], v[50:51]
	v_pk_fma_f32 v[148:149], v[4:5], v[132:133], v[52:53]
	v_pk_fma_f32 v[150:151], v[6:7], v[134:135], v[54:55]
	v_pk_fma_f32 v[152:153], v[8:9], v[136:137], v[56:57]
	v_pk_fma_f32 v[154:155], v[26:27], v[138:139], v[58:59]
	v_pk_fma_f32 v[156:157], v[28:29], v[140:141], v[60:61]
	v_pk_fma_f32 v[158:159], v[30:31], v[142:143], v[62:63]
	v_pk_fma_f32 v[160:161], v[32:33], v[144:145], v[64:65]
	v_pk_fma_f32 v[146:147], v[10:11], v[98:99], v[146:147]
	v_pk_fma_f32 v[148:149], v[12:13], v[100:101], v[148:149]
	v_pk_fma_f32 v[150:151], v[14:15], v[102:103], v[150:151]
	v_pk_fma_f32 v[152:153], v[16:17], v[104:105], v[152:153]
	v_pk_fma_f32 v[154:155], v[34:35], v[106:107], v[154:155]
	v_pk_fma_f32 v[156:157], v[36:37], v[108:109], v[156:157]
	v_pk_fma_f32 v[158:159], v[38:39], v[110:111], v[158:159]
	v_pk_fma_f32 v[160:161], v[40:41], v[112:113], v[160:161]
	v_pk_fma_f32 v[146:147], v[18:19], v[114:115], v[146:147]
	v_pk_fma_f32 v[148:149], v[20:21], v[116:117], v[148:149]
	v_pk_fma_f32 v[150:151], v[22:23], v[118:119], v[150:151]
	v_pk_fma_f32 v[152:153], v[24:25], v[120:121], v[152:153]
	v_pk_fma_f32 v[154:155], v[42:43], v[122:123], v[154:155]
	v_pk_fma_f32 v[156:157], v[44:45], v[124:125], v[156:157]
	v_pk_fma_f32 v[158:159], v[46:47], v[126:127], v[158:159]
	v_pk_fma_f32 v[160:161], v[48:49], v[128:129], v[160:161]
	v_mul_f32_e32 v162, 0xbfb8aa3b, v146
	v_mul_f32_e32 v163, 0xbfb8aa3b, v147
	v_mul_f32_e32 v164, 0xbfb8aa3b, v148
	v_mul_f32_e32 v165, 0xbfb8aa3b, v149
	v_mul_f32_e32 v166, 0xbfb8aa3b, v150
	v_mul_f32_e32 v167, 0xbfb8aa3b, v151
	v_mul_f32_e32 v168, 0xbfb8aa3b, v152
	v_mul_f32_e32 v169, 0xbfb8aa3b, v153
	v_exp_f32_e32 v162, v162
	v_exp_f32_e32 v163, v163
	v_exp_f32_e32 v164, v164
	v_exp_f32_e32 v165, v165
	v_exp_f32_e32 v166, v166
	v_exp_f32_e32 v167, v167
	v_exp_f32_e32 v168, v168
	v_exp_f32_e32 v169, v169
	v_add_f32_e32 v162, 1.0, v162
	v_add_f32_e32 v163, 1.0, v163
	v_add_f32_e32 v164, 1.0, v164
	v_add_f32_e32 v165, 1.0, v165
	v_add_f32_e32 v166, 1.0, v166
	v_add_f32_e32 v167, 1.0, v167
	v_add_f32_e32 v168, 1.0, v168
	v_add_f32_e32 v169, 1.0, v169
	v_rcp_f32_e32 v162, v162
	v_rcp_f32_e32 v163, v163
	v_rcp_f32_e32 v164, v164
	v_rcp_f32_e32 v165, v165
	v_rcp_f32_e32 v166, v166
	v_rcp_f32_e32 v167, v167
	v_rcp_f32_e32 v168, v168
	v_rcp_f32_e32 v169, v169
	s_nop 0
	v_pk_mul_f32 v[146:147], v[146:147], v[162:163]
	v_pk_mul_f32 v[148:149], v[148:149], v[164:165]
	v_pk_mul_f32 v[150:151], v[150:151], v[166:167]
	v_pk_mul_f32 v[152:153], v[152:153], v[168:169]
	v_pk_mul_f32 v[146:147], v[154:155], v[146:147]
	v_pk_mul_f32 v[148:149], v[156:157], v[148:149]
	v_pk_mul_f32 v[150:151], v[158:159], v[150:151]
	v_pk_mul_f32 v[152:153], v[160:161], v[152:153]
	v_cvt_pk_bf16_f32 v162, v146, v147
	v_cvt_pk_bf16_f32 v163, v148, v149
	v_cvt_pk_bf16_f32 v164, v150, v151
	v_cvt_pk_bf16_f32 v165, v152, v153
	global_store_dwordx4 v173, v[162:165], s[20:21]
	v_add_u32_e32 v173, 0x5600, v173
	s_waitcnt vmcnt(4)
	v_lshlrev_b32_e32 v130, 16, v74
	v_and_b32_e32 v131, 0xffff0000, v74
	v_lshlrev_b32_e32 v132, 16, v75
	v_and_b32_e32 v133, 0xffff0000, v75
	v_lshlrev_b32_e32 v134, 16, v76
	v_and_b32_e32 v135, 0xffff0000, v76
	v_lshlrev_b32_e32 v136, 16, v77
	v_and_b32_e32 v137, 0xffff0000, v77
	v_lshlrev_b32_e32 v138, 16, v78
	v_and_b32_e32 v139, 0xffff0000, v78
	v_lshlrev_b32_e32 v140, 16, v79
	v_and_b32_e32 v141, 0xffff0000, v79
	v_lshlrev_b32_e32 v142, 16, v80
	v_and_b32_e32 v143, 0xffff0000, v80
	v_lshlrev_b32_e32 v144, 16, v81
	v_and_b32_e32 v145, 0xffff0000, v81
	global_load_dwordx4 v[74:77], v172, s[16:17] nt
	global_load_dwordx4 v[78:81], v172, s[18:19] nt
	v_add_u32_e32 v172, 0xac00, v172
	v_pk_fma_f32 v[146:147], v[2:3], v[98:99], v[50:51]
	v_pk_fma_f32 v[148:149], v[4:5], v[100:101], v[52:53]
	v_pk_fma_f32 v[150:151], v[6:7], v[102:103], v[54:55]
	v_pk_fma_f32 v[152:153], v[8:9], v[104:105], v[56:57]
	v_pk_fma_f32 v[154:155], v[26:27], v[106:107], v[58:59]
	v_pk_fma_f32 v[156:157], v[28:29], v[108:109], v[60:61]
	v_pk_fma_f32 v[158:159], v[30:31], v[110:111], v[62:63]
	v_pk_fma_f32 v[160:161], v[32:33], v[112:113], v[64:65]
	v_pk_fma_f32 v[146:147], v[10:11], v[114:115], v[146:147]
	v_pk_fma_f32 v[148:149], v[12:13], v[116:117], v[148:149]
	v_pk_fma_f32 v[150:151], v[14:15], v[118:119], v[150:151]
	v_pk_fma_f32 v[152:153], v[16:17], v[120:121], v[152:153]
	v_pk_fma_f32 v[154:155], v[34:35], v[122:123], v[154:155]
	v_pk_fma_f32 v[156:157], v[36:37], v[124:125], v[156:157]
	v_pk_fma_f32 v[158:159], v[38:39], v[126:127], v[158:159]
	v_pk_fma_f32 v[160:161], v[40:41], v[128:129], v[160:161]
	v_pk_fma_f32 v[146:147], v[18:19], v[130:131], v[146:147]
	v_pk_fma_f32 v[148:149], v[20:21], v[132:133], v[148:149]
	v_pk_fma_f32 v[150:151], v[22:23], v[134:135], v[150:151]
	v_pk_fma_f32 v[152:153], v[24:25], v[136:137], v[152:153]
	v_pk_fma_f32 v[154:155], v[42:43], v[138:139], v[154:155]
	v_pk_fma_f32 v[156:157], v[44:45], v[140:141], v[156:157]
	v_pk_fma_f32 v[158:159], v[46:47], v[142:143], v[158:159]
	v_pk_fma_f32 v[160:161], v[48:49], v[144:145], v[160:161]
	v_mul_f32_e32 v162, 0xbfb8aa3b, v146
	v_mul_f32_e32 v163, 0xbfb8aa3b, v147
	v_mul_f32_e32 v164, 0xbfb8aa3b, v148
	v_mul_f32_e32 v165, 0xbfb8aa3b, v149
	v_mul_f32_e32 v166, 0xbfb8aa3b, v150
	v_mul_f32_e32 v167, 0xbfb8aa3b, v151
	v_mul_f32_e32 v168, 0xbfb8aa3b, v152
	v_mul_f32_e32 v169, 0xbfb8aa3b, v153
	v_exp_f32_e32 v162, v162
	v_exp_f32_e32 v163, v163
	v_exp_f32_e32 v164, v164
	v_exp_f32_e32 v165, v165
	v_exp_f32_e32 v166, v166
	v_exp_f32_e32 v167, v167
	v_exp_f32_e32 v168, v168
	v_exp_f32_e32 v169, v169
	v_add_f32_e32 v162, 1.0, v162
	v_add_f32_e32 v163, 1.0, v163
	v_add_f32_e32 v164, 1.0, v164
	v_add_f32_e32 v165, 1.0, v165
	v_add_f32_e32 v166, 1.0, v166
	v_add_f32_e32 v167, 1.0, v167
	v_add_f32_e32 v168, 1.0, v168
	v_add_f32_e32 v169, 1.0, v169
	v_rcp_f32_e32 v162, v162
	v_rcp_f32_e32 v163, v163
	v_rcp_f32_e32 v164, v164
	v_rcp_f32_e32 v165, v165
	v_rcp_f32_e32 v166, v166
	v_rcp_f32_e32 v167, v167
	v_rcp_f32_e32 v168, v168
	v_rcp_f32_e32 v169, v169
	s_nop 0
	v_pk_mul_f32 v[146:147], v[146:147], v[162:163]
	v_pk_mul_f32 v[148:149], v[148:149], v[164:165]
	v_pk_mul_f32 v[150:151], v[150:151], v[166:167]
	v_pk_mul_f32 v[152:153], v[152:153], v[168:169]
	v_pk_mul_f32 v[146:147], v[154:155], v[146:147]
	v_pk_mul_f32 v[148:149], v[156:157], v[148:149]
	v_pk_mul_f32 v[150:151], v[158:159], v[150:151]
	v_pk_mul_f32 v[152:153], v[160:161], v[152:153]
	v_cvt_pk_bf16_f32 v162, v146, v147
	v_cvt_pk_bf16_f32 v163, v148, v149
	v_cvt_pk_bf16_f32 v164, v150, v151
	v_cvt_pk_bf16_f32 v165, v152, v153
	global_store_dwordx4 v173, v[162:165], s[20:21]
	v_add_u32_e32 v173, 0x5600, v173
	s_waitcnt vmcnt(4)
	v_lshlrev_b32_e32 v98, 16, v66
	v_and_b32_e32 v99, 0xffff0000, v66
	v_lshlrev_b32_e32 v100, 16, v67
	v_and_b32_e32 v101, 0xffff0000, v67
	v_lshlrev_b32_e32 v102, 16, v68
	v_and_b32_e32 v103, 0xffff0000, v68
	v_lshlrev_b32_e32 v104, 16, v69
	v_and_b32_e32 v105, 0xffff0000, v69
	v_lshlrev_b32_e32 v106, 16, v70
	v_and_b32_e32 v107, 0xffff0000, v70
	v_lshlrev_b32_e32 v108, 16, v71
	v_and_b32_e32 v109, 0xffff0000, v71
	v_lshlrev_b32_e32 v110, 16, v72
	v_and_b32_e32 v111, 0xffff0000, v72
	v_lshlrev_b32_e32 v112, 16, v73
	v_and_b32_e32 v113, 0xffff0000, v73
	global_load_dwordx4 v[66:69], v172, s[16:17] nt
	global_load_dwordx4 v[70:73], v172, s[18:19] nt
	v_add_u32_e32 v172, 0xac00, v172
	v_pk_fma_f32 v[146:147], v[2:3], v[114:115], v[50:51]
	v_pk_fma_f32 v[148:149], v[4:5], v[116:117], v[52:53]
	v_pk_fma_f32 v[150:151], v[6:7], v[118:119], v[54:55]
	v_pk_fma_f32 v[152:153], v[8:9], v[120:121], v[56:57]
	v_pk_fma_f32 v[154:155], v[26:27], v[122:123], v[58:59]
	v_pk_fma_f32 v[156:157], v[28:29], v[124:125], v[60:61]
	v_pk_fma_f32 v[158:159], v[30:31], v[126:127], v[62:63]
	v_pk_fma_f32 v[160:161], v[32:33], v[128:129], v[64:65]
	v_pk_fma_f32 v[146:147], v[10:11], v[130:131], v[146:147]
	v_pk_fma_f32 v[148:149], v[12:13], v[132:133], v[148:149]
	v_pk_fma_f32 v[150:151], v[14:15], v[134:135], v[150:151]
	v_pk_fma_f32 v[152:153], v[16:17], v[136:137], v[152:153]
	v_pk_fma_f32 v[154:155], v[34:35], v[138:139], v[154:155]
	v_pk_fma_f32 v[156:157], v[36:37], v[140:141], v[156:157]
	v_pk_fma_f32 v[158:159], v[38:39], v[142:143], v[158:159]
	v_pk_fma_f32 v[160:161], v[40:41], v[144:145], v[160:161]
	v_pk_fma_f32 v[146:147], v[18:19], v[98:99], v[146:147]
	v_pk_fma_f32 v[148:149], v[20:21], v[100:101], v[148:149]
	v_pk_fma_f32 v[150:151], v[22:23], v[102:103], v[150:151]
	v_pk_fma_f32 v[152:153], v[24:25], v[104:105], v[152:153]
	v_pk_fma_f32 v[154:155], v[42:43], v[106:107], v[154:155]
	v_pk_fma_f32 v[156:157], v[44:45], v[108:109], v[156:157]
	v_pk_fma_f32 v[158:159], v[46:47], v[110:111], v[158:159]
	v_pk_fma_f32 v[160:161], v[48:49], v[112:113], v[160:161]
	v_mul_f32_e32 v162, 0xbfb8aa3b, v146
	v_mul_f32_e32 v163, 0xbfb8aa3b, v147
	v_mul_f32_e32 v164, 0xbfb8aa3b, v148
	v_mul_f32_e32 v165, 0xbfb8aa3b, v149
	v_mul_f32_e32 v166, 0xbfb8aa3b, v150
	v_mul_f32_e32 v167, 0xbfb8aa3b, v151
	v_mul_f32_e32 v168, 0xbfb8aa3b, v152
	v_mul_f32_e32 v169, 0xbfb8aa3b, v153
	v_exp_f32_e32 v162, v162
	v_exp_f32_e32 v163, v163
	v_exp_f32_e32 v164, v164
	v_exp_f32_e32 v165, v165
	v_exp_f32_e32 v166, v166
	v_exp_f32_e32 v167, v167
	v_exp_f32_e32 v168, v168
	v_exp_f32_e32 v169, v169
	v_add_f32_e32 v162, 1.0, v162
	v_add_f32_e32 v163, 1.0, v163
	v_add_f32_e32 v164, 1.0, v164
	v_add_f32_e32 v165, 1.0, v165
	v_add_f32_e32 v166, 1.0, v166
	v_add_f32_e32 v167, 1.0, v167
	v_add_f32_e32 v168, 1.0, v168
	v_add_f32_e32 v169, 1.0, v169
	v_rcp_f32_e32 v162, v162
	v_rcp_f32_e32 v163, v163
	v_rcp_f32_e32 v164, v164
	v_rcp_f32_e32 v165, v165
	v_rcp_f32_e32 v166, v166
	v_rcp_f32_e32 v167, v167
	v_rcp_f32_e32 v168, v168
	v_rcp_f32_e32 v169, v169
	s_nop 0
	v_pk_mul_f32 v[146:147], v[146:147], v[162:163]
	v_pk_mul_f32 v[148:149], v[148:149], v[164:165]
	v_pk_mul_f32 v[150:151], v[150:151], v[166:167]
	v_pk_mul_f32 v[152:153], v[152:153], v[168:169]
	v_pk_mul_f32 v[146:147], v[154:155], v[146:147]
	v_pk_mul_f32 v[148:149], v[156:157], v[148:149]
	v_pk_mul_f32 v[150:151], v[158:159], v[150:151]
	v_pk_mul_f32 v[152:153], v[160:161], v[152:153]
	v_cvt_pk_bf16_f32 v162, v146, v147
	v_cvt_pk_bf16_f32 v163, v148, v149
	v_cvt_pk_bf16_f32 v164, v150, v151
	v_cvt_pk_bf16_f32 v165, v152, v153
	global_store_dwordx4 v173, v[162:165], s[20:21]
	v_add_u32_e32 v173, 0x5600, v173
	s_waitcnt vmcnt(4)
	v_lshlrev_b32_e32 v114, 16, v74
	v_and_b32_e32 v115, 0xffff0000, v74
	v_lshlrev_b32_e32 v116, 16, v75
	v_and_b32_e32 v117, 0xffff0000, v75
	v_lshlrev_b32_e32 v118, 16, v76
	v_and_b32_e32 v119, 0xffff0000, v76
	v_lshlrev_b32_e32 v120, 16, v77
	v_and_b32_e32 v121, 0xffff0000, v77
	v_lshlrev_b32_e32 v122, 16, v78
	v_and_b32_e32 v123, 0xffff0000, v78
	v_lshlrev_b32_e32 v124, 16, v79
	v_and_b32_e32 v125, 0xffff0000, v79
	v_lshlrev_b32_e32 v126, 16, v80
	v_and_b32_e32 v127, 0xffff0000, v80
	v_lshlrev_b32_e32 v128, 16, v81
	v_and_b32_e32 v129, 0xffff0000, v81
	global_load_dwordx4 v[74:77], v172, s[16:17] nt
	global_load_dwordx4 v[78:81], v172, s[18:19] nt
	v_add_u32_e32 v172, 0xac00, v172
	v_pk_fma_f32 v[146:147], v[2:3], v[130:131], v[50:51]
	v_pk_fma_f32 v[148:149], v[4:5], v[132:133], v[52:53]
	v_pk_fma_f32 v[150:151], v[6:7], v[134:135], v[54:55]
	v_pk_fma_f32 v[152:153], v[8:9], v[136:137], v[56:57]
	v_pk_fma_f32 v[154:155], v[26:27], v[138:139], v[58:59]
	v_pk_fma_f32 v[156:157], v[28:29], v[140:141], v[60:61]
	v_pk_fma_f32 v[158:159], v[30:31], v[142:143], v[62:63]
	v_pk_fma_f32 v[160:161], v[32:33], v[144:145], v[64:65]
	v_pk_fma_f32 v[146:147], v[10:11], v[98:99], v[146:147]
	v_pk_fma_f32 v[148:149], v[12:13], v[100:101], v[148:149]
	v_pk_fma_f32 v[150:151], v[14:15], v[102:103], v[150:151]
	v_pk_fma_f32 v[152:153], v[16:17], v[104:105], v[152:153]
	v_pk_fma_f32 v[154:155], v[34:35], v[106:107], v[154:155]
	v_pk_fma_f32 v[156:157], v[36:37], v[108:109], v[156:157]
	v_pk_fma_f32 v[158:159], v[38:39], v[110:111], v[158:159]
	v_pk_fma_f32 v[160:161], v[40:41], v[112:113], v[160:161]
	v_pk_fma_f32 v[146:147], v[18:19], v[114:115], v[146:147]
	v_pk_fma_f32 v[148:149], v[20:21], v[116:117], v[148:149]
	v_pk_fma_f32 v[150:151], v[22:23], v[118:119], v[150:151]
	v_pk_fma_f32 v[152:153], v[24:25], v[120:121], v[152:153]
	v_pk_fma_f32 v[154:155], v[42:43], v[122:123], v[154:155]
	v_pk_fma_f32 v[156:157], v[44:45], v[124:125], v[156:157]
	v_pk_fma_f32 v[158:159], v[46:47], v[126:127], v[158:159]
	v_pk_fma_f32 v[160:161], v[48:49], v[128:129], v[160:161]
	v_mul_f32_e32 v162, 0xbfb8aa3b, v146
	v_mul_f32_e32 v163, 0xbfb8aa3b, v147
	v_mul_f32_e32 v164, 0xbfb8aa3b, v148
	v_mul_f32_e32 v165, 0xbfb8aa3b, v149
	v_mul_f32_e32 v166, 0xbfb8aa3b, v150
	v_mul_f32_e32 v167, 0xbfb8aa3b, v151
	v_mul_f32_e32 v168, 0xbfb8aa3b, v152
	v_mul_f32_e32 v169, 0xbfb8aa3b, v153
	v_exp_f32_e32 v162, v162
	v_exp_f32_e32 v163, v163
	v_exp_f32_e32 v164, v164
	v_exp_f32_e32 v165, v165
	v_exp_f32_e32 v166, v166
	v_exp_f32_e32 v167, v167
	v_exp_f32_e32 v168, v168
	v_exp_f32_e32 v169, v169
	v_add_f32_e32 v162, 1.0, v162
	v_add_f32_e32 v163, 1.0, v163
	v_add_f32_e32 v164, 1.0, v164
	v_add_f32_e32 v165, 1.0, v165
	v_add_f32_e32 v166, 1.0, v166
	v_add_f32_e32 v167, 1.0, v167
	v_add_f32_e32 v168, 1.0, v168
	v_add_f32_e32 v169, 1.0, v169
	v_rcp_f32_e32 v162, v162
	v_rcp_f32_e32 v163, v163
	v_rcp_f32_e32 v164, v164
	v_rcp_f32_e32 v165, v165
	v_rcp_f32_e32 v166, v166
	v_rcp_f32_e32 v167, v167
	v_rcp_f32_e32 v168, v168
	v_rcp_f32_e32 v169, v169
	s_nop 0
	v_pk_mul_f32 v[146:147], v[146:147], v[162:163]
	v_pk_mul_f32 v[148:149], v[148:149], v[164:165]
	v_pk_mul_f32 v[150:151], v[150:151], v[166:167]
	v_pk_mul_f32 v[152:153], v[152:153], v[168:169]
	v_pk_mul_f32 v[146:147], v[154:155], v[146:147]
	v_pk_mul_f32 v[148:149], v[156:157], v[148:149]
	v_pk_mul_f32 v[150:151], v[158:159], v[150:151]
	v_pk_mul_f32 v[152:153], v[160:161], v[152:153]
	v_cvt_pk_bf16_f32 v162, v146, v147
	v_cvt_pk_bf16_f32 v163, v148, v149
	v_cvt_pk_bf16_f32 v164, v150, v151
	v_cvt_pk_bf16_f32 v165, v152, v153
	global_store_dwordx4 v173, v[162:165], s[20:21]
	v_add_u32_e32 v173, 0x5600, v173
	s_waitcnt vmcnt(4)
	v_lshlrev_b32_e32 v130, 16, v66
	v_and_b32_e32 v131, 0xffff0000, v66
	v_lshlrev_b32_e32 v132, 16, v67
	v_and_b32_e32 v133, 0xffff0000, v67
	v_lshlrev_b32_e32 v134, 16, v68
	v_and_b32_e32 v135, 0xffff0000, v68
	v_lshlrev_b32_e32 v136, 16, v69
	v_and_b32_e32 v137, 0xffff0000, v69
	v_lshlrev_b32_e32 v138, 16, v70
	v_and_b32_e32 v139, 0xffff0000, v70
	v_lshlrev_b32_e32 v140, 16, v71
	v_and_b32_e32 v141, 0xffff0000, v71
	v_lshlrev_b32_e32 v142, 16, v72
	v_and_b32_e32 v143, 0xffff0000, v72
	v_lshlrev_b32_e32 v144, 16, v73
	v_and_b32_e32 v145, 0xffff0000, v73
	global_load_dwordx4 v[66:69], v172, s[16:17] nt
	global_load_dwordx4 v[70:73], v172, s[18:19] nt
	v_add_u32_e32 v172, 0xac00, v172
	v_pk_fma_f32 v[146:147], v[2:3], v[98:99], v[50:51]
	v_pk_fma_f32 v[148:149], v[4:5], v[100:101], v[52:53]
	v_pk_fma_f32 v[150:151], v[6:7], v[102:103], v[54:55]
	v_pk_fma_f32 v[152:153], v[8:9], v[104:105], v[56:57]
	v_pk_fma_f32 v[154:155], v[26:27], v[106:107], v[58:59]
	v_pk_fma_f32 v[156:157], v[28:29], v[108:109], v[60:61]
	v_pk_fma_f32 v[158:159], v[30:31], v[110:111], v[62:63]
	v_pk_fma_f32 v[160:161], v[32:33], v[112:113], v[64:65]
	v_pk_fma_f32 v[146:147], v[10:11], v[114:115], v[146:147]
	v_pk_fma_f32 v[148:149], v[12:13], v[116:117], v[148:149]
	v_pk_fma_f32 v[150:151], v[14:15], v[118:119], v[150:151]
	v_pk_fma_f32 v[152:153], v[16:17], v[120:121], v[152:153]
	v_pk_fma_f32 v[154:155], v[34:35], v[122:123], v[154:155]
	v_pk_fma_f32 v[156:157], v[36:37], v[124:125], v[156:157]
	v_pk_fma_f32 v[158:159], v[38:39], v[126:127], v[158:159]
	v_pk_fma_f32 v[160:161], v[40:41], v[128:129], v[160:161]
	v_pk_fma_f32 v[146:147], v[18:19], v[130:131], v[146:147]
	v_pk_fma_f32 v[148:149], v[20:21], v[132:133], v[148:149]
	v_pk_fma_f32 v[150:151], v[22:23], v[134:135], v[150:151]
	v_pk_fma_f32 v[152:153], v[24:25], v[136:137], v[152:153]
	v_pk_fma_f32 v[154:155], v[42:43], v[138:139], v[154:155]
	v_pk_fma_f32 v[156:157], v[44:45], v[140:141], v[156:157]
	v_pk_fma_f32 v[158:159], v[46:47], v[142:143], v[158:159]
	v_pk_fma_f32 v[160:161], v[48:49], v[144:145], v[160:161]
	v_mul_f32_e32 v162, 0xbfb8aa3b, v146
	v_mul_f32_e32 v163, 0xbfb8aa3b, v147
	v_mul_f32_e32 v164, 0xbfb8aa3b, v148
	v_mul_f32_e32 v165, 0xbfb8aa3b, v149
	v_mul_f32_e32 v166, 0xbfb8aa3b, v150
	v_mul_f32_e32 v167, 0xbfb8aa3b, v151
	v_mul_f32_e32 v168, 0xbfb8aa3b, v152
	v_mul_f32_e32 v169, 0xbfb8aa3b, v153
	v_exp_f32_e32 v162, v162
	v_exp_f32_e32 v163, v163
	v_exp_f32_e32 v164, v164
	v_exp_f32_e32 v165, v165
	v_exp_f32_e32 v166, v166
	v_exp_f32_e32 v167, v167
	v_exp_f32_e32 v168, v168
	v_exp_f32_e32 v169, v169
	v_add_f32_e32 v162, 1.0, v162
	v_add_f32_e32 v163, 1.0, v163
	v_add_f32_e32 v164, 1.0, v164
	v_add_f32_e32 v165, 1.0, v165
	v_add_f32_e32 v166, 1.0, v166
	v_add_f32_e32 v167, 1.0, v167
	v_add_f32_e32 v168, 1.0, v168
	v_add_f32_e32 v169, 1.0, v169
	v_rcp_f32_e32 v162, v162
	v_rcp_f32_e32 v163, v163
	v_rcp_f32_e32 v164, v164
	v_rcp_f32_e32 v165, v165
	v_rcp_f32_e32 v166, v166
	v_rcp_f32_e32 v167, v167
	v_rcp_f32_e32 v168, v168
	v_rcp_f32_e32 v169, v169
	s_nop 0
	v_pk_mul_f32 v[146:147], v[146:147], v[162:163]
	v_pk_mul_f32 v[148:149], v[148:149], v[164:165]
	v_pk_mul_f32 v[150:151], v[150:151], v[166:167]
	v_pk_mul_f32 v[152:153], v[152:153], v[168:169]
	v_pk_mul_f32 v[146:147], v[154:155], v[146:147]
	v_pk_mul_f32 v[148:149], v[156:157], v[148:149]
	v_pk_mul_f32 v[150:151], v[158:159], v[150:151]
	v_pk_mul_f32 v[152:153], v[160:161], v[152:153]
	v_cvt_pk_bf16_f32 v162, v146, v147
	v_cvt_pk_bf16_f32 v163, v148, v149
	v_cvt_pk_bf16_f32 v164, v150, v151
	v_cvt_pk_bf16_f32 v165, v152, v153
	global_store_dwordx4 v173, v[162:165], s[20:21]
	v_add_u32_e32 v173, 0x5600, v173
	s_waitcnt vmcnt(4)
	v_lshlrev_b32_e32 v98, 16, v74
	v_and_b32_e32 v99, 0xffff0000, v74
	v_lshlrev_b32_e32 v100, 16, v75
	v_and_b32_e32 v101, 0xffff0000, v75
	v_lshlrev_b32_e32 v102, 16, v76
	v_and_b32_e32 v103, 0xffff0000, v76
	v_lshlrev_b32_e32 v104, 16, v77
	v_and_b32_e32 v105, 0xffff0000, v77
	v_lshlrev_b32_e32 v106, 16, v78
	v_and_b32_e32 v107, 0xffff0000, v78
	v_lshlrev_b32_e32 v108, 16, v79
	v_and_b32_e32 v109, 0xffff0000, v79
	v_lshlrev_b32_e32 v110, 16, v80
	v_and_b32_e32 v111, 0xffff0000, v80
	v_lshlrev_b32_e32 v112, 16, v81
	v_and_b32_e32 v113, 0xffff0000, v81
	global_load_dwordx4 v[74:77], v172, s[16:17] nt
	global_load_dwordx4 v[78:81], v172, s[18:19] nt
	v_add_u32_e32 v172, 0xac00, v172
	v_pk_fma_f32 v[146:147], v[2:3], v[114:115], v[50:51]
	v_pk_fma_f32 v[148:149], v[4:5], v[116:117], v[52:53]
	v_pk_fma_f32 v[150:151], v[6:7], v[118:119], v[54:55]
	v_pk_fma_f32 v[152:153], v[8:9], v[120:121], v[56:57]
	v_pk_fma_f32 v[154:155], v[26:27], v[122:123], v[58:59]
	v_pk_fma_f32 v[156:157], v[28:29], v[124:125], v[60:61]
	v_pk_fma_f32 v[158:159], v[30:31], v[126:127], v[62:63]
	v_pk_fma_f32 v[160:161], v[32:33], v[128:129], v[64:65]
	v_pk_fma_f32 v[146:147], v[10:11], v[130:131], v[146:147]
	v_pk_fma_f32 v[148:149], v[12:13], v[132:133], v[148:149]
	v_pk_fma_f32 v[150:151], v[14:15], v[134:135], v[150:151]
	v_pk_fma_f32 v[152:153], v[16:17], v[136:137], v[152:153]
	v_pk_fma_f32 v[154:155], v[34:35], v[138:139], v[154:155]
	v_pk_fma_f32 v[156:157], v[36:37], v[140:141], v[156:157]
	v_pk_fma_f32 v[158:159], v[38:39], v[142:143], v[158:159]
	v_pk_fma_f32 v[160:161], v[40:41], v[144:145], v[160:161]
	v_pk_fma_f32 v[146:147], v[18:19], v[98:99], v[146:147]
	v_pk_fma_f32 v[148:149], v[20:21], v[100:101], v[148:149]
	v_pk_fma_f32 v[150:151], v[22:23], v[102:103], v[150:151]
	v_pk_fma_f32 v[152:153], v[24:25], v[104:105], v[152:153]
	v_pk_fma_f32 v[154:155], v[42:43], v[106:107], v[154:155]
	v_pk_fma_f32 v[156:157], v[44:45], v[108:109], v[156:157]
	v_pk_fma_f32 v[158:159], v[46:47], v[110:111], v[158:159]
	v_pk_fma_f32 v[160:161], v[48:49], v[112:113], v[160:161]
	v_mul_f32_e32 v162, 0xbfb8aa3b, v146
	v_mul_f32_e32 v163, 0xbfb8aa3b, v147
	v_mul_f32_e32 v164, 0xbfb8aa3b, v148
	v_mul_f32_e32 v165, 0xbfb8aa3b, v149
	v_mul_f32_e32 v166, 0xbfb8aa3b, v150
	v_mul_f32_e32 v167, 0xbfb8aa3b, v151
	v_mul_f32_e32 v168, 0xbfb8aa3b, v152
	v_mul_f32_e32 v169, 0xbfb8aa3b, v153
	v_exp_f32_e32 v162, v162
	v_exp_f32_e32 v163, v163
	v_exp_f32_e32 v164, v164
	v_exp_f32_e32 v165, v165
	v_exp_f32_e32 v166, v166
	v_exp_f32_e32 v167, v167
	v_exp_f32_e32 v168, v168
	v_exp_f32_e32 v169, v169
	v_add_f32_e32 v162, 1.0, v162
	v_add_f32_e32 v163, 1.0, v163
	v_add_f32_e32 v164, 1.0, v164
	v_add_f32_e32 v165, 1.0, v165
	v_add_f32_e32 v166, 1.0, v166
	v_add_f32_e32 v167, 1.0, v167
	v_add_f32_e32 v168, 1.0, v168
	v_add_f32_e32 v169, 1.0, v169
	v_rcp_f32_e32 v162, v162
	v_rcp_f32_e32 v163, v163
	v_rcp_f32_e32 v164, v164
	v_rcp_f32_e32 v165, v165
	v_rcp_f32_e32 v166, v166
	v_rcp_f32_e32 v167, v167
	v_rcp_f32_e32 v168, v168
	v_rcp_f32_e32 v169, v169
	s_nop 0
	v_pk_mul_f32 v[146:147], v[146:147], v[162:163]
	v_pk_mul_f32 v[148:149], v[148:149], v[164:165]
	v_pk_mul_f32 v[150:151], v[150:151], v[166:167]
	v_pk_mul_f32 v[152:153], v[152:153], v[168:169]
	v_pk_mul_f32 v[146:147], v[154:155], v[146:147]
	v_pk_mul_f32 v[148:149], v[156:157], v[148:149]
	v_pk_mul_f32 v[150:151], v[158:159], v[150:151]
	v_pk_mul_f32 v[152:153], v[160:161], v[152:153]
	v_cvt_pk_bf16_f32 v162, v146, v147
	v_cvt_pk_bf16_f32 v163, v148, v149
	v_cvt_pk_bf16_f32 v164, v150, v151
	v_cvt_pk_bf16_f32 v165, v152, v153
	global_store_dwordx4 v173, v[162:165], s[20:21]
	v_add_u32_e32 v173, 0x5600, v173
	v_mov_b32_e32 v114, v98
	v_mov_b32_e32 v115, v99
	v_mov_b32_e32 v116, v100
	v_mov_b32_e32 v117, v101
	v_mov_b32_e32 v118, v102
	v_mov_b32_e32 v119, v103
	v_mov_b32_e32 v120, v104
	v_mov_b32_e32 v121, v105
	v_mov_b32_e32 v122, v106
	v_mov_b32_e32 v123, v107
	v_mov_b32_e32 v124, v108
	v_mov_b32_e32 v125, v109
	v_mov_b32_e32 v126, v110
	v_mov_b32_e32 v127, v111
	v_mov_b32_e32 v128, v112
	v_mov_b32_e32 v129, v113
	v_mov_b32_e32 v98, v130
	v_mov_b32_e32 v99, v131
	v_mov_b32_e32 v100, v132
	v_mov_b32_e32 v101, v133
	v_mov_b32_e32 v102, v134
	v_mov_b32_e32 v103, v135
	v_mov_b32_e32 v104, v136
	v_mov_b32_e32 v105, v137
	v_mov_b32_e32 v106, v138
	v_mov_b32_e32 v107, v139
	v_mov_b32_e32 v108, v140
	v_mov_b32_e32 v109, v141
	v_mov_b32_e32 v110, v142
	v_mov_b32_e32 v111, v143
	v_mov_b32_e32 v112, v144
	v_mov_b32_e32 v113, v145
	s_sub_u32 s22, s22, 1
	s_cmp_lg_u32 s22, 0
	s_cbranch_scc1 .Lgrp_cy0
	s_waitcnt vmcnt(0)
	v_lshrrev_b32_e32 v1, 6, v0
	v_lshlrev_b32_e32 v1, 14, v1
	v_and_b32_e32 v2, 63, v0
	v_lshl_or_b32 v1, v2, 4, v1
	ds_read_b128 v[138:141], v1
	ds_read_b128 v[142:145], v1 offset:1024
	ds_read_b128 v[146:149], v1 offset:2048
	ds_read_b128 v[150:153], v1 offset:3072
	ds_read_b128 v[154:157], v1 offset:4096
	ds_read_b128 v[158:161], v1 offset:5120
	ds_read_b128 v[162:165], v1 offset:6144
	ds_read_b128 v[166:169], v1 offset:7168
	ds_read_b128 v[170:173], v1 offset:8192
	ds_read_b128 v[174:177], v1 offset:9216
	ds_read_b128 v[178:181], v1 offset:10240
	ds_read_b128 v[182:185], v1 offset:11264
	ds_read_b128 v[186:189], v1 offset:12288
	ds_read_b128 v[190:193], v1 offset:13312
	ds_read_b128 v[194:197], v1 offset:14336
	ds_read_b128 v[198:201], v1 offset:15360
	s_waitcnt lgkmcnt(0)

.LBB0_1768:
	s_cmp_lt_i32 s62, 23
	s_cselect_b64 s[0:1], -1, 0
	s_and_b64 s[2:3], s[0:1], s[2:3]
	s_andn2_b64 vcc, exec, s[2:3]
	s_cbranch_vccnz .LBB0_1781
	s_lshl_b32 s6, s88, 9
	v_or_b32_e32 v1, s6, v0
	s_mov_b32 s2, 0x158000
	v_cmp_gt_i32_e32 vcc, s2, v1
	s_and_saveexec_b64 s[2:3], vcc
	s_cbranch_execz .LBB0_1780
	s_waitcnt vmcnt(0) lgkmcnt(0)
	v_lshrrev_b32_e32 v1, 6, v0
	v_lshlrev_b32_e32 v1, 14, v1
	v_and_b32_e32 v2, 63, v0
	v_lshl_or_b32 v1, v2, 4, v1
	ds_write_b128 v1, v[138:141]
	ds_write_b128 v1, v[142:145] offset:1024
	ds_write_b128 v1, v[146:149] offset:2048
	ds_write_b128 v1, v[150:153] offset:3072
	ds_write_b128 v1, v[154:157] offset:4096
	ds_write_b128 v1, v[158:161] offset:5120
	ds_write_b128 v1, v[162:165] offset:6144
	ds_write_b128 v1, v[166:169] offset:7168
	ds_write_b128 v1, v[170:173] offset:8192
	ds_write_b128 v1, v[174:177] offset:9216
	ds_write_b128 v1, v[178:181] offset:10240
	ds_write_b128 v1, v[182:185] offset:11264
	ds_write_b128 v1, v[186:189] offset:12288
	ds_write_b128 v1, v[190:193] offset:13312
	ds_write_b128 v1, v[194:197] offset:14336
	ds_write_b128 v1, v[198:201] offset:15360
	v_readlane_b32 s24, v247, 3
	v_readlane_b32 s25, v247, 4
	s_load_dwordx4 s[8:11], s[24:25], 0xd0
	s_waitcnt lgkmcnt(0)
	s_add_u32 s12, s10, 0x15800
	s_addc_u32 s13, s11, 0
	s_add_u32 s14, s12, 0xac00
	s_addc_u32 s15, s13, 0
	s_add_u32 s8, s8, 0x40800
	s_addc_u32 s9, s9, 0
	s_add_u32 s10, s8, 0xac00
	s_addc_u32 s11, s9, 0
	s_mov_b64 s[16:17], s[70:71]
	s_add_u32 s18, s70, 0x5600
	s_addc_u32 s19, s71, 0
	s_add_u32 s20, s94, 0x72500000
	s_addc_u32 s21, s95, 0
	s_mov_b32 s23, 0x56000
	s_mov_b32 s28, 0x2b000
	s_mov_b32 s22, 11
	s_lshl_b32 s24, s88, 9
	v_add_u32_e32 v1, s24, v0
	v_lshrrev_b32_e32 v175, 5, v1
	v_mov_b32_e32 v178, 0xbe83
	v_mul_lo_u32 v175, v175, v178
	v_lshrrev_b32_e32 v175, 21, v175
	v_mul_u32_u24_e32 v178, 0x560, v175
	v_sub_u32_e32 v170, v1, v178
	v_min_u32_e32 v175, 94, v175
	v_mul_u32_u24_e32 v175, 0xac7, v175
	v_lshrrev_b32_e32 v171, 8, v175
	v_lshlrev_b32_e32 v175, 4, v170
	v_mad_u32_u24 v172, v171, s23, v175
	v_mad_u32_u24 v173, v171, s28, v175
	v_lshlrev_b32_e32 v174, 5, v170
	v_add_u32_e32 v176, 0x15800, v174
	v_add_u32_e32 v177, 0x2b000, v174
	global_load_dwordx4 v[2:5], v174, s[8:9]
	global_load_dwordx4 v[6:9], v174, s[8:9] offset:16
	global_load_dwordx4 v[10:13], v176, s[8:9]
	global_load_dwordx4 v[14:17], v176, s[8:9] offset:16
	global_load_dwordx4 v[18:21], v177, s[8:9]
	global_load_dwordx4 v[22:25], v177, s[8:9] offset:16
	global_load_dwordx4 v[50:53], v174, s[12:13]
	global_load_dwordx4 v[54:57], v174, s[12:13] offset:16
	global_load_dwordx4 v[26:29], v174, s[10:11]
	global_load_dwordx4 v[30:33], v174, s[10:11] offset:16
	global_load_dwordx4 v[34:37], v176, s[10:11]
	global_load_dwordx4 v[38:41], v176, s[10:11] offset:16
	global_load_dwordx4 v[42:45], v177, s[10:11]
	global_load_dwordx4 v[46:49], v177, s[10:11] offset:16
	global_load_dwordx4 v[58:61], v174, s[14:15]
	global_load_dwordx4 v[62:65], v174, s[14:15] offset:16
	v_and_b32_e32 v175, 0xff, v171
	v_cmp_ne_u32_e32 vcc, 0, v175
	v_mov_b32_e32 v178, 0x15800
	s_nop 0
	v_cndmask_b32_e32 v175, 0, v178, vcc
	v_sub_u32_e32 v176, v172, v175
	v_lshrrev_b32_e32 v175, 1, v175
	v_sub_u32_e32 v177, v172, v175
	global_load_dwordx4 v[66:69], v176, s[16:17] nt
	global_load_dwordx4 v[70:73], v176, s[18:19] nt
	global_load_dwordx4 v[74:77], v177, s[16:17] nt
	global_load_dwordx4 v[78:81], v177, s[18:19] nt
	s_waitcnt vmcnt(0)
	v_lshlrev_b32_e32 v98, 16, v66
	v_and_b32_e32 v99, 0xffff0000, v66
	v_lshlrev_b32_e32 v100, 16, v67
	v_and_b32_e32 v101, 0xffff0000, v67
	v_lshlrev_b32_e32 v102, 16, v68
	v_and_b32_e32 v103, 0xffff0000, v68
	v_lshlrev_b32_e32 v104, 16, v69
	v_and_b32_e32 v105, 0xffff0000, v69
	v_lshlrev_b32_e32 v106, 16, v70
	v_and_b32_e32 v107, 0xffff0000, v70
	v_lshlrev_b32_e32 v108, 16, v71
	v_and_b32_e32 v109, 0xffff0000, v71
	v_lshlrev_b32_e32 v110, 16, v72
	v_and_b32_e32 v111, 0xffff0000, v72
	v_lshlrev_b32_e32 v112, 16, v73
	v_and_b32_e32 v113, 0xffff0000, v73
	v_lshlrev_b32_e32 v114, 16, v74
	v_and_b32_e32 v115, 0xffff0000, v74
	v_lshlrev_b32_e32 v116, 16, v75
	v_and_b32_e32 v117, 0xffff0000, v75
	v_lshlrev_b32_e32 v118, 16, v76
	v_and_b32_e32 v119, 0xffff0000, v76
	v_lshlrev_b32_e32 v120, 16, v77
	v_and_b32_e32 v121, 0xffff0000, v77
	v_lshlrev_b32_e32 v122, 16, v78
	v_and_b32_e32 v123, 0xffff0000, v78
	v_lshlrev_b32_e32 v124, 16, v79
	v_and_b32_e32 v125, 0xffff0000, v79
	v_lshlrev_b32_e32 v126, 16, v80
	v_and_b32_e32 v127, 0xffff0000, v80
	v_lshlrev_b32_e32 v128, 16, v81
	v_and_b32_e32 v129, 0xffff0000, v81
	global_load_dwordx4 v[66:69], v172, s[16:17] nt
	global_load_dwordx4 v[70:73], v172, s[18:19] nt
	v_add_u32_e32 v172, 0xac00, v172
	global_load_dwordx4 v[74:77], v172, s[16:17] nt
	global_load_dwordx4 v[78:81], v172, s[18:19] nt
	v_add_u32_e32 v172, 0xac00, v172
	s_waitcnt vmcnt(0)
